# E1 L0: skip first two counted vmcnt waits of each unit after an epilogue (all earlier DMA already landed)
# speedup vs baseline: 1.0070x; 1.0070x over previous
; #define PG8_STAGE(bufoff, gbase, voff) do { _Pragma("unroll") for (int _i = 0; _i < 2; ++_i) \
;         __builtin_amdgcn_global_load_lds((const unsigned*)((const char*)(gbase) + (voff)[_i]), (LAS unsigned*)(lds + (bufoff) + ldsw + _i * 8192), 16, 0, 0); } while (0)
; #define PG8_WAIT_V(n) asm volatile("s_waitcnt vmcnt(" #n ")" ::: "memory")
; #define PG8_BAR __builtin_amdgcn_s_barrier()
; template <class Epi, class Sched>
; __device__ __forceinline__ void gemm_phase(LAS unsigned char* lds, const int K, const int lda, const int ldb, const Sched& S, const Epi& E) {
;     int tid = threadIdx.x; asm volatile("" : "+v"(tid));
;     const int wid = __builtin_amdgcn_readfirstlane(tid >> 6), lane = tid & 63, wr = wid >> 2, wc = wid & 3, fr = lane & 15, fq = lane >> 4;
;     const int nt = K / BK;
;     unsigned voffA[2], voffB[2];
; #pragma unroll
;     for (int i = 0; i < 2; ++i) { int R, C; stage_rc(tid * 16 + i * 8192, R, C); const int Rb = (R & ~31) + perm32(R & 31);
;         voffA[i] = (unsigned)(R * lda + C) * 2u; voffB[i] = (unsigned)(Rb * ldb + C) * 2u; }
;     const size_t kstep = (size_t)(BK * 2);
;     const size_t hA = (size_t)HALF * lda * 2, hB = (size_t)HALF * ldb * 2;
;     const unsigned ldsw = (unsigned)wid * 1024u;
;     const int aoff = lds_byte(wr * 64 + fr, fq * 8), boff = lds_byte(wc * 32 + fr, fq * 8);
;     ...
;     Unit cur, nxt; int ui = 0;
;     if (!S.next(0, cur)) return;
;     f32x4 acc[2][2][4][2];
; #pragma unroll
;     for (int a = 0; a < 2; ++a)
; #pragma unroll
;         for (int b = 0; b < 2; ++b)
; #pragma unroll
;             for (int m = 0; m < 4; ++m)
; #pragma unroll
;                 for (int n = 0; n < 2; ++n) acc[a][b][m][n] = (f32x4){0.f, 0.f, 0.f, 0.f};
;     bf16x8 At[4][2], B0[2][2], B1[2][2];
;     const char* cA = S.aptr(cur); const char* cB = S.bptr(cur);
;     PG8_STAGE(PG8_SB(0, 0), cB, voffB); PG8_STAGE(PG8_SB(0, 1), cB + hB, voffB); PG8_STAGE(PG8_SA(0, 0), cA, voffA); PG8_STAGE(PG8_SA(0, 1), cA + hA, voffA);
;     if (wr == 1) PG8_BAR;
;     PG8_WAIT_V(2); PG8_BAR;
;     PG8_STAGE(PG8_SB(1, 0), cB + kstep, voffB); PG8_STAGE(PG8_SA(1, 0), cA + kstep, voffA); PG8_STAGE(PG8_SB(1, 1), cB + hB + kstep, voffB);
;     PG8_WAIT_V(6); PG8_BAR;
.LBB0_203:
	v_and_b32_e32 v157, 15, v10
	v_and_b32_e32 v17, 48, v10
	v_lshlrev_b32_e32 v18, 2, v10
	s_mov_b64 s[22:23], 0x80
	s_sext_i32_i16 s0, s4
	s_and_b32 s4, s18, 3
	s_lshl_b32 s7, s19, 13
	v_lshl_or_b32 v17, v157, 6, v17
	v_and_b32_e32 v18, 32, v18
	s_add_i32 m0, s1, 0x18000
	v_lshl_add_u64 v[6:7], v[6:7], 0, s[22:23]
	s_lshl_b32 s35, s19, 6
	v_bitop3_b32 v19, v17, s7, v18 bitop3:0xde
	s_lshl_b32 s7, s4, 5
	s_lshl_b32 s19, s4, 12
	s_waitcnt vmcnt(2)
	s_barrier
	global_load_lds_dwordx4 v[6:7], off
	v_lshl_add_u64 v[4:5], v[4:5], 0, s[22:23]
	s_add_i32 m0, s1, 0x1a000
	s_add_i32 s38, s1, 0x8000
	s_add_i32 s39, s1, 0xa000
	global_load_lds_dwordx4 v[4:5], off
	v_lshl_add_u64 v[0:1], v[0:1], 0, s[22:23]
	s_mov_b32 m0, s38
	s_add_u32 s24, s54, 0x80080
	global_load_lds_dwordx4 v[0:1], off
	v_lshl_add_u64 v[0:1], v[2:3], 0, s[22:23]
	s_mov_b32 m0, s39
	s_addc_u32 s25, s55, 0
	global_load_lds_dwordx4 v[0:1], off
	s_add_i32 m0, s1, 0x1c000
	v_lshl_add_u64 v[0:1], s[24:25], 0, v[132:133]
	global_load_lds_dwordx4 v[0:1], off
	v_lshl_add_u64 v[0:1], s[24:25], 0, v[128:129]
	s_add_i32 m0, s1, 0x1e000
	s_cmpk_lt_u32 s5, 0x100
	global_load_lds_dwordx4 v[0:1], off
	v_lshlrev_b32_e32 v26, 15, v8
	s_cselect_b64 s[24:25], -1, 0
	s_lshl_b32 s5, s18, 12
	v_and_b32_e32 v26, 0xffff0000, v26
	s_add_i32 s5, s5, 0
	v_lshl_add_u32 v9, v9, 12, v26
	v_and_b32_e32 v8, 1, v8
	s_add_i32 s5, s5, 0x20000
	v_lshl_or_b32 v8, v8, 6, v9
	s_add_u32 s41, s36, 0x1ce00000
	v_lshlrev_b32_e32 v0, 1, v10
	v_lshl_add_u32 v138, v11, 1, v8
	v_lshlrev_b32_e32 v8, 15, v13
	v_bfe_u32 v15, v10, 4, 2
	s_addc_u32 s62, s37, 0
	v_and_b32_e32 v0, 14, v0
	v_bfe_u32 v2, v10, 3, 1
	v_and_b32_e32 v8, 0xffff0000, v8
	s_add_u32 s63, s36, 0x14e00000
	v_add_u32_e32 v0, s5, v0
	v_bitop3_b32 v4, v2, v15, 2 bitop3:0x36
	v_lshl_add_u32 v8, v12, 12, v8
	v_and_b32_e32 v9, 1, v13
	s_addc_u32 s64, s37, 0
	v_xor_b32_e32 v3, v2, v15
	v_lshl_add_u32 v5, v4, 4, v0
	v_bitop3_b32 v4, v2, v15, 4 bitop3:0x36
	v_bitop3_b32 v2, v2, v15, 6 bitop3:0x36
	v_lshl_or_b32 v8, v9, 6, v8
	v_and_b32_e32 v159, 63, v10
	v_lshlrev_b32_e32 v16, 3, v15
	s_add_u32 s65, s36, 0xae00000
	v_lshlrev_b32_e32 v1, 10, v15
	v_lshl_add_u32 v15, v2, 4, v0
	v_and_b32_e32 v2, 7, v10
	v_bfe_u32 v10, v10, 3, 3
	v_lshl_add_u32 v140, v14, 1, v8
	v_mbcnt_lo_u32_b32 v8, -1, 0
	v_bitop3_b32 v161, v17, s19, v18 bitop3:0xde
	s_waitcnt vmcnt(6)
	s_addc_u32 s66, s37, 0
	s_lshl_b32 s4, s4, 20
	v_lshl_add_u32 v3, v3, 4, v0
	v_lshl_add_u32 v7, v4, 4, v0
	v_lshlrev_b32_e32 v0, 3, v2
	v_lshl_add_u32 v17, v10, 7, s5
	v_lshlrev_b32_e32 v18, 4, v2
	v_lshlrev_b32_e32 v2, 15, v10
	v_or_b32_e32 v4, 8, v10
	v_or_b32_e32 v6, 16, v10
	v_or_b32_e32 v10, 24, v10
	v_mbcnt_hi_u32_b32 v8, -1, v8
	v_lshl_add_u32 v20, v4, 7, s5
	v_xor_b32_e32 v21, 16, v18
	v_lshlrev_b32_e32 v4, 15, v4
	v_lshl_add_u32 v22, v6, 7, s5
	v_xor_b32_e32 v23, 32, v18
	v_lshlrev_b32_e32 v6, 15, v6
	v_lshl_add_u32 v24, v10, 7, s5
	v_xor_b32_e32 v25, 48, v18
	v_lshlrev_b32_e32 v10, 15, v10
	s_or_b32 s5, s4, 0x400000
	s_add_i32 s68, 0, 0x10000
	s_add_i32 s69, 0, 0x14000
	v_and_or_b32 v8, v8, 64, v157
	s_mov_b32 s21, 0
	s_ashr_i32 s67, s3, 31
	v_mov_b32_e32 v139, v137
	v_mov_b32_e32 v141, v137
	s_mov_b64 s[26:27], 0x100
	v_add_u32_e32 v163, 0, v19
	v_lshlrev_b32_e32 v165, 2, v8
	s_mov_b32 s28, 0x3a000000
	s_mov_b32 s70, 0x800000
	v_lshlrev_b32_e32 v136, 1, v0
	v_add_u32_e32 v167, v3, v1
	v_add_u32_e32 v169, v5, v1
	v_add_u32_e32 v171, v7, v1
	v_add_u32_e32 v173, v15, v1
	s_lshl_b32 s42, s4, 1
	v_add_u32_e32 v184, v17, v18
	v_lshlrev_b32_e32 v142, 1, v2
	v_add_u32_e32 v185, v20, v21
	v_lshlrev_b32_e32 v144, 1, v4
	v_add_u32_e32 v186, v22, v23
	v_lshlrev_b32_e32 v146, 1, v6
	v_add_u32_e32 v187, v24, v25
	v_lshlrev_b32_e32 v148, 1, v10
	s_lshl_b32 s44, s5, 1
	s_lshl_b32 s71, s7, 1
	v_lshlrev_b32_e32 v150, 1, v16
	v_mov_b64_e32 v[152:153], 0xa00
	v_mov_b64_e32 v[154:155], 0x9ff
	v_add_u32_e32 v188, s68, v161
	v_add_u32_e32 v189, s69, v161
	v_mov_b32_e32 v156, 0x358637bd
	s_mov_b32 s99, 0
	s_mov_b32 s72, 0
	s_barrier
	s_branch .LBB0_206
.LBB0_204:
	s_mov_b64 s[4:5], 0
	s_mov_b32 s99, 1

; #define PG8_STAGE(bufoff, gbase, voff) do { _Pragma("unroll") for (int _i = 0; _i < 2; ++_i) \
;         __builtin_amdgcn_global_load_lds((const unsigned*)((const char*)(gbase) + (voff)[_i]), (LAS unsigned*)(lds + (bufoff) + ldsw + _i * 8192), 16, 0, 0); } while (0)
; #define PG8_LDA(dst, b, h) do { _Pragma("unroll") for (int m = 0; m < 4; ++m) _Pragma("unroll") for (int k = 0; k < 2; ++k) dst[m][k] = *(const LAS bf16x8*)(lds + PG8_SA(b, h) + aoff + m * 2048 + k * 1024); } while (0)
; #define PG8_LDB(dst, b, h) do { _Pragma("unroll") for (int n = 0; n < 2; ++n) _Pragma("unroll") for (int k = 0; k < 2; ++k) dst[n][k] = *(const LAS bf16x8*)(lds + PG8_SB(b, h) + boff + n * 2048 + k * 1024); } while (0)
; #define PG8_MMA(ai, bj, At, Bt) do { __builtin_amdgcn_s_setprio(1); _Pragma("unroll") for (int m = 0; m < 4; ++m) _Pragma("unroll") for (int n = 0; n < 2; ++n) _Pragma("unroll") for (int k = 0; k < 2; ++k) \
;         acc[ai][bj][m][n] = __builtin_amdgcn_mfma_f32_16x16x32_bf16(Bt[n][k], At[m][k], acc[ai][bj][m][n], 0, 0, 0); __builtin_amdgcn_s_setprio(0); } while (0)
; #define PG8_WAIT_V(n) asm volatile("s_waitcnt vmcnt(" #n ")" ::: "memory")
; #define PG8_WAIT_L(n) asm volatile("s_waitcnt lgkmcnt(" #n ")" ::: "memory")
; #define PG8_BAR __builtin_amdgcn_s_barrier()
; #define PG8_SCHED __builtin_amdgcn_sched_barrier(0)
; template <class Epi, class Sched>
; __device__ __forceinline__ void gemm_phase(LAS unsigned char* lds, const int K, const int lda, const int ldb, const Sched& S, const Epi& E) {
;     ...
;             const char* a1 = cA + (size_t)(t + 1) * kstep;
;             const char* a2 = last ? nA : cA + (size_t)(t + 2) * kstep; const char* b2 = last ? nB : cB + (size_t)(t + 2) * kstep;
;             const char* a3 = a2 + kstep; const char* b3 = b2 + kstep;
;             PG8_LDB(B0, 0, 0); PG8_LDB(B1, 0, 1); PG8_SCHED; PG8_LDA(At, 0, 0); PG8_STAGE(PG8_SA(1, 1), a1 + hA, voffA);
;             PG8_WAIT_V(8); PG8_WAIT_L(0); PG8_BAR; PG8_MMA(0, 0, At, B0); PG8_MMA(0, 1, At, B1); PG8_BAR; PG8_SCHED;
;             PG8_LDA(At, 0, 1); PG8_STAGE(PG8_SB(0, 0), b2, voffB); PG8_STAGE(PG8_SB(0, 1), b2 + hB, voffB); PG8_STAGE(PG8_SA(0, 0), a2, voffA);
;             PG8_WAIT_V(8); PG8_WAIT_L(0); PG8_BAR; PG8_MMA(1, 0, At, B0); PG8_MMA(1, 1, At, B1); PG8_BAR; PG8_SCHED;
.LBB0_209:
	ds_read_b128 v[174:177], v188
	ds_read_b128 v[178:181], v188 offset:1024
	ds_read_b128 v[190:193], v188 offset:2048
	ds_read_b128 v[194:197], v188 offset:3072
	ds_read_b128 v[198:201], v189
	ds_read_b128 v[202:205], v189 offset:1024
	ds_read_b128 v[206:209], v189 offset:2048
	ds_read_b128 v[210:213], v189 offset:3072
	s_add_u32 s49, s54, 0xfff80080
	s_addc_u32 s56, s55, -1
	s_cmp_eq_u32 s47, 28
	s_cselect_b32 s59, s7, s56
	s_cselect_b32 s58, s18, s49
	s_cselect_b32 s57, s19, s45
	s_cselect_b32 s56, s20, s43
	v_lshl_add_u64 v[182:183], s[54:55], 0, v[140:141]
	s_add_i32 m0, s1, 0xc000
	ds_read_b128 v[214:217], v163
	ds_read_b128 v[218:221], v163 offset:1024
	ds_read_b128 v[222:225], v163 offset:2048
	ds_read_b128 v[226:229], v163 offset:3072
	ds_read_b128 v[230:233], v163 offset:4096
	ds_read_b128 v[236:239], v163 offset:5120
	ds_read_b128 v[240:243], v163 offset:6144
	ds_read_b128 v[244:247], v163 offset:7168
	global_load_lds_dwordx4 v[182:183], off
	v_lshl_add_u64 v[182:183], s[54:55], 0, v[138:139]
	s_add_i32 m0, s1, 0xe000
	s_nop 0
	global_load_lds_dwordx4 v[182:183], off
	s_cmp_lg_u32 s99, 0
	s_cbranch_scc1 .Lrw0_a
	s_waitcnt vmcnt(8)
.Lrw0_a:
	s_waitcnt lgkmcnt(0)
	s_barrier
	s_setprio 1
	s_waitcnt lgkmcnt(0)
	v_mfma_f32_16x16x32_bf16 v[124:127], v[174:177], v[214:217], v[124:127]
	v_mfma_f32_16x16x32_bf16 v[120:123], v[190:193], v[214:217], v[120:123]
	v_mfma_f32_16x16x32_bf16 v[108:111], v[174:177], v[222:225], v[108:111]
	v_mfma_f32_16x16x32_bf16 v[104:107], v[190:193], v[222:225], v[104:107]
	v_mfma_f32_16x16x32_bf16 v[92:95], v[174:177], v[230:233], v[92:95]
	v_mfma_f32_16x16x32_bf16 v[88:91], v[190:193], v[230:233], v[88:91]
	v_mfma_f32_16x16x32_bf16 v[76:79], v[174:177], v[240:243], v[76:79]
	v_mfma_f32_16x16x32_bf16 v[72:75], v[190:193], v[240:243], v[72:75]
	v_mfma_f32_16x16x32_bf16 v[124:127], v[178:181], v[218:221], v[124:127]
	v_mfma_f32_16x16x32_bf16 v[120:123], v[194:197], v[218:221], v[120:123]
	v_mfma_f32_16x16x32_bf16 v[108:111], v[178:181], v[226:229], v[108:111]
	v_mfma_f32_16x16x32_bf16 v[104:107], v[194:197], v[226:229], v[104:107]
	v_mfma_f32_16x16x32_bf16 v[92:95], v[178:181], v[236:239], v[92:95]
	v_mfma_f32_16x16x32_bf16 v[88:91], v[194:197], v[236:239], v[88:91]
	v_mfma_f32_16x16x32_bf16 v[76:79], v[178:181], v[244:247], v[76:79]
	v_mfma_f32_16x16x32_bf16 v[72:75], v[194:197], v[244:247], v[72:75]
	s_setprio 0
	s_setprio 1
	v_mfma_f32_16x16x32_bf16 v[116:119], v[198:201], v[214:217], v[116:119]
	v_mfma_f32_16x16x32_bf16 v[112:115], v[206:209], v[214:217], v[112:115]
	v_mfma_f32_16x16x32_bf16 v[100:103], v[198:201], v[222:225], v[100:103]
	v_mfma_f32_16x16x32_bf16 v[96:99], v[206:209], v[222:225], v[96:99]
	v_mfma_f32_16x16x32_bf16 v[84:87], v[198:201], v[230:233], v[84:87]
	v_mfma_f32_16x16x32_bf16 v[80:83], v[206:209], v[230:233], v[80:83]
	v_mfma_f32_16x16x32_bf16 v[68:71], v[198:201], v[240:243], v[68:71]
	v_mfma_f32_16x16x32_bf16 v[64:67], v[206:209], v[240:243], v[64:67]
	v_mfma_f32_16x16x32_bf16 v[116:119], v[202:205], v[218:221], v[116:119]
	v_mfma_f32_16x16x32_bf16 v[112:115], v[210:213], v[218:221], v[112:115]
	v_mfma_f32_16x16x32_bf16 v[100:103], v[202:205], v[226:229], v[100:103]
	v_mfma_f32_16x16x32_bf16 v[96:99], v[210:213], v[226:229], v[96:99]
	v_mfma_f32_16x16x32_bf16 v[84:87], v[202:205], v[236:239], v[84:87]
	v_mfma_f32_16x16x32_bf16 v[80:83], v[210:213], v[236:239], v[80:83]
	v_mfma_f32_16x16x32_bf16 v[68:71], v[202:205], v[244:247], v[68:71]
	v_mfma_f32_16x16x32_bf16 v[64:67], v[210:213], v[244:247], v[64:67]
	s_setprio 0
	s_barrier
	s_add_i32 s49, s68, s2
	v_lshl_add_u64 v[182:183], s[56:57], 0, v[132:133]
	s_mov_b32 m0, s49
	ds_read_b128 v[214:217], v163 offset:16384
	ds_read_b128 v[218:221], v163 offset:17408
	ds_read_b128 v[222:225], v163 offset:18432
	ds_read_b128 v[226:229], v163 offset:19456
	ds_read_b128 v[230:233], v163 offset:20480
	ds_read_b128 v[236:239], v163 offset:21504
	ds_read_b128 v[240:243], v163 offset:22528
	ds_read_b128 v[244:247], v163 offset:23552
	global_load_lds_dwordx4 v[182:183], off
	s_add_i32 m0, s49, 0x2000
	s_add_u32 s60, s56, 0x80000
	v_lshl_add_u64 v[248:249], s[56:57], 0, v[128:129]
	s_addc_u32 s61, s57, 0
	s_add_i32 s49, s69, s2
	global_load_lds_dwordx4 v[248:249], off
	v_lshl_add_u64 v[250:251], s[60:61], 0, v[132:133]
	s_mov_b32 m0, s49
	v_lshl_add_u64 v[252:253], s[58:59], 0, v[130:131]
	global_load_lds_dwordx4 v[250:251], off
	v_lshl_add_u64 v[250:251], s[60:61], 0, v[128:129]
	s_add_i32 m0, s49, 0x2000
	s_nop 0
	global_load_lds_dwordx4 v[250:251], off
	v_lshl_add_u64 v[250:251], s[58:59], 0, v[134:135]
	s_mov_b32 m0, s1
	s_nop 0
	global_load_lds_dwordx4 v[250:251], off
	s_mov_b32 m0, s17
	s_nop 0
	global_load_lds_dwordx4 v[252:253], off
	s_cmp_lg_u32 s99, 0
	s_cbranch_scc1 .Lrw0_b
	s_waitcnt vmcnt(8)
; #define PG8_STAGE(bufoff, gbase, voff) do { _Pragma("unroll") for (int _i = 0; _i < 2; ++_i) \
;         __builtin_amdgcn_global_load_lds((const unsigned*)((const char*)(gbase) + (voff)[_i]), (LAS unsigned*)(lds + (bufoff) + ldsw + _i * 8192), 16, 0, 0); } while (0)
; #define PG8_LDA(dst, b, h) do { _Pragma("unroll") for (int m = 0; m < 4; ++m) _Pragma("unroll") for (int k = 0; k < 2; ++k) dst[m][k] = *(const LAS bf16x8*)(lds + PG8_SA(b, h) + aoff + m * 2048 + k * 1024); } while (0)
; #define PG8_LDB(dst, b, h) do { _Pragma("unroll") for (int n = 0; n < 2; ++n) _Pragma("unroll") for (int k = 0; k < 2; ++k) dst[n][k] = *(const LAS bf16x8*)(lds + PG8_SB(b, h) + boff + n * 2048 + k * 1024); } while (0)
; #define PG8_MMA(ai, bj, At, Bt) do { __builtin_amdgcn_s_setprio(1); _Pragma("unroll") for (int m = 0; m < 4; ++m) _Pragma("unroll") for (int n = 0; n < 2; ++n) _Pragma("unroll") for (int k = 0; k < 2; ++k) \
;         acc[ai][bj][m][n] = __builtin_amdgcn_mfma_f32_16x16x32_bf16(Bt[n][k], At[m][k], acc[ai][bj][m][n], 0, 0, 0); __builtin_amdgcn_s_setprio(0); } while (0)
; #define PG8_WAIT_V(n) asm volatile("s_waitcnt vmcnt(" #n ")" ::: "memory")
; #define PG8_WAIT_L(n) asm volatile("s_waitcnt lgkmcnt(" #n ")" ::: "memory")
; #define PG8_BAR __builtin_amdgcn_s_barrier()
; #define PG8_SCHED __builtin_amdgcn_sched_barrier(0)
; template <class Epi, class Sched>
; __device__ __forceinline__ void gemm_phase(LAS unsigned char* lds, const int K, const int lda, const int ldb, const Sched& S, const Epi& E) {
;     ...
;             PG8_WAIT_V(8); PG8_WAIT_L(0); PG8_BAR; PG8_MMA(1, 0, At, B0); PG8_MMA(1, 1, At, B1); PG8_BAR; PG8_SCHED;
;             PG8_LDB(B0, 1, 0); PG8_LDB(B1, 1, 1); PG8_SCHED; PG8_LDA(At, 1, 0); PG8_STAGE(PG8_SA(0, 1), a2 + hA, voffA);
;             PG8_WAIT_V(8); PG8_WAIT_L(0); PG8_BAR; PG8_MMA(0, 0, At, B0); PG8_MMA(0, 1, At, B1); PG8_BAR; PG8_SCHED;
;             PG8_LDA(At, 1, 1); PG8_STAGE(PG8_SB(1, 0), b3, voffB); PG8_STAGE(PG8_SB(1, 1), b3 + hB, voffB); PG8_STAGE(PG8_SA(1, 0), a3, voffA);
.Lrw0_b:
	s_mov_b32 s99, 0
	s_waitcnt lgkmcnt(0)
	s_barrier
	s_setprio 1
	s_waitcnt lgkmcnt(0)
	v_mfma_f32_16x16x32_bf16 v[60:63], v[174:177], v[214:217], v[60:63]
	v_mfma_f32_16x16x32_bf16 v[56:59], v[190:193], v[214:217], v[56:59]
	v_mfma_f32_16x16x32_bf16 v[44:47], v[174:177], v[222:225], v[44:47]
	v_mfma_f32_16x16x32_bf16 v[40:43], v[190:193], v[222:225], v[40:43]
	v_mfma_f32_16x16x32_bf16 v[28:31], v[174:177], v[230:233], v[28:31]
	v_mfma_f32_16x16x32_bf16 v[24:27], v[190:193], v[230:233], v[24:27]
	v_mfma_f32_16x16x32_bf16 v[12:15], v[174:177], v[240:243], v[12:15]
	v_mfma_f32_16x16x32_bf16 v[8:11], v[190:193], v[240:243], v[8:11]
	v_mfma_f32_16x16x32_bf16 v[60:63], v[178:181], v[218:221], v[60:63]
	v_mfma_f32_16x16x32_bf16 v[56:59], v[194:197], v[218:221], v[56:59]
	v_mfma_f32_16x16x32_bf16 v[44:47], v[178:181], v[226:229], v[44:47]
	v_mfma_f32_16x16x32_bf16 v[40:43], v[194:197], v[226:229], v[40:43]
	v_mfma_f32_16x16x32_bf16 v[28:31], v[178:181], v[236:239], v[28:31]
	v_mfma_f32_16x16x32_bf16 v[24:27], v[194:197], v[236:239], v[24:27]
	v_mfma_f32_16x16x32_bf16 v[12:15], v[178:181], v[244:247], v[12:15]
	v_mfma_f32_16x16x32_bf16 v[8:11], v[194:197], v[244:247], v[8:11]
	s_setprio 0
	s_setprio 1
	v_mfma_f32_16x16x32_bf16 v[52:55], v[198:201], v[214:217], v[52:55]
	v_mfma_f32_16x16x32_bf16 v[48:51], v[206:209], v[214:217], v[48:51]
	v_mfma_f32_16x16x32_bf16 v[36:39], v[198:201], v[222:225], v[36:39]
	v_mfma_f32_16x16x32_bf16 v[32:35], v[206:209], v[222:225], v[32:35]
	v_mfma_f32_16x16x32_bf16 v[20:23], v[198:201], v[230:233], v[20:23]
	v_mfma_f32_16x16x32_bf16 v[16:19], v[206:209], v[230:233], v[16:19]
	v_mfma_f32_16x16x32_bf16 v[4:7], v[198:201], v[240:243], v[4:7]
	v_mfma_f32_16x16x32_bf16 v[0:3], v[206:209], v[240:243], v[0:3]
	v_mfma_f32_16x16x32_bf16 v[52:55], v[202:205], v[218:221], v[52:55]
	v_mfma_f32_16x16x32_bf16 v[48:51], v[210:213], v[218:221], v[48:51]
	v_mfma_f32_16x16x32_bf16 v[36:39], v[202:205], v[226:229], v[36:39]
	v_mfma_f32_16x16x32_bf16 v[32:35], v[210:213], v[226:229], v[32:35]
	v_mfma_f32_16x16x32_bf16 v[20:23], v[202:205], v[236:239], v[20:23]
	v_mfma_f32_16x16x32_bf16 v[16:19], v[210:213], v[236:239], v[16:19]
	v_mfma_f32_16x16x32_bf16 v[4:7], v[202:205], v[244:247], v[4:7]
	v_mfma_f32_16x16x32_bf16 v[0:3], v[210:213], v[244:247], v[0:3]
	s_setprio 0
	s_barrier
	s_add_i32 s49, 0, 0x18000
	v_add_u32_e32 v143, s49, v161
	s_add_i32 s60, 0, 0x1c000
	ds_read_b128 v[174:177], v143
	ds_read_b128 v[178:181], v143 offset:1024
	ds_read_b128 v[190:193], v143 offset:2048
	ds_read_b128 v[194:197], v143 offset:3072
	v_add_u32_e32 v143, s60, v161
	ds_read_b128 v[198:201], v143
	ds_read_b128 v[202:205], v143 offset:1024
	ds_read_b128 v[206:209], v143 offset:2048
	ds_read_b128 v[210:213], v143 offset:3072
	s_add_u32 s58, s58, 0x80000
	s_addc_u32 s59, s59, 0
	s_mov_b32 m0, s29
	v_lshl_add_u64 v[234:235], s[58:59], 0, v[134:135]
	ds_read_b128 v[214:217], v163 offset:32768
	ds_read_b128 v[218:221], v163 offset:33792
	ds_read_b128 v[222:225], v163 offset:34816
	ds_read_b128 v[226:229], v163 offset:35840
	ds_read_b128 v[230:233], v163 offset:36864
	ds_read_b128 v[236:239], v163 offset:37888
	ds_read_b128 v[240:243], v163 offset:38912
	ds_read_b128 v[244:247], v163 offset:39936
	global_load_lds_dwordx4 v[234:235], off
	v_lshl_add_u64 v[234:235], s[58:59], 0, v[130:131]
	s_mov_b32 m0, s34
	s_nop 0
	global_load_lds_dwordx4 v[234:235], off
	s_waitcnt vmcnt(8)
	s_waitcnt lgkmcnt(0)
	s_barrier
	s_setprio 1
	s_waitcnt lgkmcnt(0)
	v_mfma_f32_16x16x32_bf16 v[124:127], v[174:177], v[214:217], v[124:127]
	v_mfma_f32_16x16x32_bf16 v[120:123], v[190:193], v[214:217], v[120:123]
	v_mfma_f32_16x16x32_bf16 v[108:111], v[174:177], v[222:225], v[108:111]
	v_mfma_f32_16x16x32_bf16 v[104:107], v[190:193], v[222:225], v[104:107]
	v_mfma_f32_16x16x32_bf16 v[92:95], v[174:177], v[230:233], v[92:95]
	v_mfma_f32_16x16x32_bf16 v[88:91], v[190:193], v[230:233], v[88:91]
	v_mfma_f32_16x16x32_bf16 v[76:79], v[174:177], v[240:243], v[76:79]
	v_mfma_f32_16x16x32_bf16 v[72:75], v[190:193], v[240:243], v[72:75]
	v_mfma_f32_16x16x32_bf16 v[124:127], v[178:181], v[218:221], v[124:127]
	v_mfma_f32_16x16x32_bf16 v[120:123], v[194:197], v[218:221], v[120:123]
	v_mfma_f32_16x16x32_bf16 v[108:111], v[178:181], v[226:229], v[108:111]
	v_mfma_f32_16x16x32_bf16 v[104:107], v[194:197], v[226:229], v[104:107]
	v_mfma_f32_16x16x32_bf16 v[92:95], v[178:181], v[236:239], v[92:95]
	v_mfma_f32_16x16x32_bf16 v[88:91], v[194:197], v[236:239], v[88:91]
	v_mfma_f32_16x16x32_bf16 v[76:79], v[178:181], v[244:247], v[76:79]
	v_mfma_f32_16x16x32_bf16 v[72:75], v[194:197], v[244:247], v[72:75]
	s_setprio 0
	s_setprio 1
	v_mfma_f32_16x16x32_bf16 v[116:119], v[198:201], v[214:217], v[116:119]
	v_mfma_f32_16x16x32_bf16 v[112:115], v[206:209], v[214:217], v[112:115]
	v_mfma_f32_16x16x32_bf16 v[100:103], v[198:201], v[222:225], v[100:103]
	v_mfma_f32_16x16x32_bf16 v[96:99], v[206:209], v[222:225], v[96:99]
	v_mfma_f32_16x16x32_bf16 v[84:87], v[198:201], v[230:233], v[84:87]
	v_mfma_f32_16x16x32_bf16 v[80:83], v[206:209], v[230:233], v[80:83]
	v_mfma_f32_16x16x32_bf16 v[68:71], v[198:201], v[240:243], v[68:71]
	v_mfma_f32_16x16x32_bf16 v[64:67], v[206:209], v[240:243], v[64:67]
	v_mfma_f32_16x16x32_bf16 v[116:119], v[202:205], v[218:221], v[116:119]
	v_mfma_f32_16x16x32_bf16 v[112:115], v[210:213], v[218:221], v[112:115]
	v_mfma_f32_16x16x32_bf16 v[100:103], v[202:205], v[226:229], v[100:103]
	v_mfma_f32_16x16x32_bf16 v[96:99], v[210:213], v[226:229], v[96:99]
	v_mfma_f32_16x16x32_bf16 v[84:87], v[202:205], v[236:239], v[84:87]
	v_mfma_f32_16x16x32_bf16 v[80:83], v[210:213], v[236:239], v[80:83]
	v_mfma_f32_16x16x32_bf16 v[68:71], v[202:205], v[244:247], v[68:71]
	v_mfma_f32_16x16x32_bf16 v[64:67], v[210:213], v[244:247], v[64:67]
	s_setprio 0
	s_barrier
; #define PG8_STAGE(bufoff, gbase, voff) do { _Pragma("unroll") for (int _i = 0; _i < 2; ++_i) \
;         __builtin_amdgcn_global_load_lds((const unsigned*)((const char*)(gbase) + (voff)[_i]), (LAS unsigned*)(lds + (bufoff) + ldsw + _i * 8192), 16, 0, 0); } while (0)
; #define PG8_LDA(dst, b, h) do { _Pragma("unroll") for (int m = 0; m < 4; ++m) _Pragma("unroll") for (int k = 0; k < 2; ++k) dst[m][k] = *(const LAS bf16x8*)(lds + PG8_SA(b, h) + aoff + m * 2048 + k * 1024); } while (0)
; #define PG8_MMA(ai, bj, At, Bt) do { __builtin_amdgcn_s_setprio(1); _Pragma("unroll") for (int m = 0; m < 4; ++m) _Pragma("unroll") for (int n = 0; n < 2; ++n) _Pragma("unroll") for (int k = 0; k < 2; ++k) \
;         acc[ai][bj][m][n] = __builtin_amdgcn_mfma_f32_16x16x32_bf16(Bt[n][k], At[m][k], acc[ai][bj][m][n], 0, 0, 0); __builtin_amdgcn_s_setprio(0); } while (0)
; #define PG8_WAIT_V(n) asm volatile("s_waitcnt vmcnt(" #n ")" ::: "memory")
; #define PG8_WAIT_L(n) asm volatile("s_waitcnt lgkmcnt(" #n ")" ::: "memory")
; #define PG8_BAR __builtin_amdgcn_s_barrier()
; #define PG8_SCHED __builtin_amdgcn_sched_barrier(0)
; template <class Epi, class Sched>
; __device__ __forceinline__ void gemm_phase(LAS unsigned char* lds, const int K, const int lda, const int ldb, const Sched& S, const Epi& E) {
;     ...
;             PG8_LDA(At, 1, 1); PG8_STAGE(PG8_SB(1, 0), b3, voffB); PG8_STAGE(PG8_SB(1, 1), b3 + hB, voffB); PG8_STAGE(PG8_SA(1, 0), a3, voffA);
;             PG8_WAIT_V(8); PG8_WAIT_L(0); PG8_BAR; PG8_MMA(1, 0, At, B0); PG8_MMA(1, 1, At, B1); PG8_BAR; PG8_SCHED;
;         }
	s_add_i32 s49, s49, s2
	v_lshl_add_u64 v[182:183], v[182:183], 0, s[22:23]
	s_mov_b32 m0, s49
	ds_read_b128 v[214:217], v163 offset:49152
	ds_read_b128 v[218:221], v163 offset:50176
	ds_read_b128 v[222:225], v163 offset:51200
	ds_read_b128 v[226:229], v163 offset:52224
	ds_read_b128 v[230:233], v163 offset:53248
	ds_read_b128 v[236:239], v163 offset:54272
	ds_read_b128 v[240:243], v163 offset:55296
	ds_read_b128 v[244:247], v163 offset:56320
	global_load_lds_dwordx4 v[182:183], off
	s_add_i32 m0, s49, 0x2000
	s_add_u32 s56, s56, 0x80080
	v_lshl_add_u64 v[182:183], v[248:249], 0, s[22:23]
	s_addc_u32 s57, s57, 0
	s_add_i32 s49, s60, s2
	global_load_lds_dwordx4 v[182:183], off
	v_lshl_add_u64 v[182:183], s[56:57], 0, v[132:133]
	s_mov_b32 m0, s49
	s_nop 0
	global_load_lds_dwordx4 v[182:183], off
	v_lshl_add_u64 v[182:183], s[56:57], 0, v[128:129]
	s_add_i32 m0, s49, 0x2000
	s_nop 0
	global_load_lds_dwordx4 v[182:183], off
	v_lshl_add_u64 v[182:183], v[250:251], 0, s[22:23]
	s_mov_b32 m0, s38
	s_nop 0
	global_load_lds_dwordx4 v[182:183], off
	v_lshl_add_u64 v[182:183], v[252:253], 0, s[22:23]
	s_mov_b32 m0, s39
	s_nop 0
	global_load_lds_dwordx4 v[182:183], off
	s_waitcnt vmcnt(8)
	s_waitcnt lgkmcnt(0)
	s_barrier
	s_setprio 1
	s_waitcnt lgkmcnt(0)
	v_mfma_f32_16x16x32_bf16 v[60:63], v[174:177], v[214:217], v[60:63]
	v_mfma_f32_16x16x32_bf16 v[56:59], v[190:193], v[214:217], v[56:59]
	v_mfma_f32_16x16x32_bf16 v[44:47], v[174:177], v[222:225], v[44:47]
	v_mfma_f32_16x16x32_bf16 v[40:43], v[190:193], v[222:225], v[40:43]
	v_mfma_f32_16x16x32_bf16 v[28:31], v[174:177], v[230:233], v[28:31]
	v_mfma_f32_16x16x32_bf16 v[24:27], v[190:193], v[230:233], v[24:27]
	v_mfma_f32_16x16x32_bf16 v[12:15], v[174:177], v[240:243], v[12:15]
	v_mfma_f32_16x16x32_bf16 v[8:11], v[190:193], v[240:243], v[8:11]
	v_mfma_f32_16x16x32_bf16 v[60:63], v[178:181], v[218:221], v[60:63]
	v_mfma_f32_16x16x32_bf16 v[56:59], v[194:197], v[218:221], v[56:59]
	v_mfma_f32_16x16x32_bf16 v[44:47], v[178:181], v[226:229], v[44:47]
	v_mfma_f32_16x16x32_bf16 v[40:43], v[194:197], v[226:229], v[40:43]
	v_mfma_f32_16x16x32_bf16 v[28:31], v[178:181], v[236:239], v[28:31]
	v_mfma_f32_16x16x32_bf16 v[24:27], v[194:197], v[236:239], v[24:27]
	v_mfma_f32_16x16x32_bf16 v[12:15], v[178:181], v[244:247], v[12:15]
	v_mfma_f32_16x16x32_bf16 v[8:11], v[194:197], v[244:247], v[8:11]
	s_setprio 0
	s_setprio 1
	v_mfma_f32_16x16x32_bf16 v[52:55], v[198:201], v[214:217], v[52:55]
	v_mfma_f32_16x16x32_bf16 v[48:51], v[206:209], v[214:217], v[48:51]
	v_mfma_f32_16x16x32_bf16 v[36:39], v[198:201], v[222:225], v[36:39]
	v_mfma_f32_16x16x32_bf16 v[32:35], v[206:209], v[222:225], v[32:35]
	v_mfma_f32_16x16x32_bf16 v[20:23], v[198:201], v[230:233], v[20:23]
	v_mfma_f32_16x16x32_bf16 v[16:19], v[206:209], v[230:233], v[16:19]
	v_mfma_f32_16x16x32_bf16 v[4:7], v[198:201], v[240:243], v[4:7]
	v_mfma_f32_16x16x32_bf16 v[0:3], v[206:209], v[240:243], v[0:3]
	v_mfma_f32_16x16x32_bf16 v[52:55], v[202:205], v[218:221], v[52:55]
	v_mfma_f32_16x16x32_bf16 v[48:51], v[210:213], v[218:221], v[48:51]
	v_mfma_f32_16x16x32_bf16 v[36:39], v[202:205], v[226:229], v[36:39]
	v_mfma_f32_16x16x32_bf16 v[32:35], v[210:213], v[226:229], v[32:35]
	v_mfma_f32_16x16x32_bf16 v[20:23], v[202:205], v[236:239], v[20:23]
	v_mfma_f32_16x16x32_bf16 v[16:19], v[210:213], v[236:239], v[16:19]
	v_mfma_f32_16x16x32_bf16 v[4:7], v[202:205], v[244:247], v[4:7]
	v_mfma_f32_16x16x32_bf16 v[0:3], v[210:213], v[244:247], v[0:3]
	s_setprio 0
	s_barrier
	s_add_i32 s47, s47, 2
	s_add_u32 s43, s43, 0x100
	s_addc_u32 s45, s45, 0
	s_add_u32 s54, s54, 0x100
	s_addc_u32 s55, s55, 0
	s_cmp_gt_u32 s47, 29
	s_cbranch_scc0 .LBB0_209
	s_and_b64 vcc, exec, s[24:25]
	s_cbranch_vccz .LBB0_212
	s_barrier
